# grid barrier polling: s_sleep 1 -> s_sleep 0 in the four wait loops (size-neutral)
# speedup vs baseline: 1.0029x; 1.0029x over previous
.LBB0_506:
	s_sleep 0
	global_load_dword v1, v129, s[12:13] offset:32 sc1
	s_waitcnt vmcnt(0)
	v_and_b32_e32 v1, 0xffff0000, v1
	v_cmp_ne_u32_e32 vcc, v1, v0
	s_or_b64 s[14:15], vcc, s[14:15]
	s_andn2_b64 exec, exec, s[14:15]
	s_cbranch_execnz .LBB0_506

.LBB0_513:
	v_readlane_b32 s4, v253, 11
	v_readlane_b32 s5, v253, 12
	v_readlane_b32 s1, v255, 2
	s_mov_b64 s[12:13], -1
	s_mov_b64 s[14:15], -1
	s_waitcnt lgkmcnt(0)
	s_nop 0
	global_load_dword v0, v129, s[4:5] sc1
	v_readlane_b32 s4, v253, 13
	v_readlane_b32 s5, v253, 14
	s_nop 4
	global_load_dword v1, v129, s[4:5] sc1
	v_readlane_b32 s4, v253, 15
	v_readlane_b32 s5, v253, 16
	s_waitcnt vmcnt(0)
	v_add_u32_e32 v16, v1, v0
	s_nop 2
	global_load_dword v2, v129, s[4:5] sc1
	v_readlane_b32 s4, v253, 17
	v_readlane_b32 s5, v253, 18
	s_waitcnt vmcnt(0)
	v_add_u32_e32 v16, v16, v2
	s_nop 2
	global_load_dword v3, v129, s[4:5] sc1
	v_readlane_b32 s4, v253, 19
	v_readlane_b32 s5, v253, 20
	s_waitcnt vmcnt(0)
	v_add_u32_e32 v16, v16, v3
	s_nop 2
	global_load_dword v4, v129, s[4:5] sc1
	v_readlane_b32 s4, v253, 21
	v_readlane_b32 s5, v253, 22
	s_waitcnt vmcnt(0)
	v_add_u32_e32 v16, v16, v4
	s_nop 2
	global_load_dword v5, v129, s[4:5] sc1
	v_readlane_b32 s4, v253, 23
	v_readlane_b32 s5, v253, 24
	s_waitcnt vmcnt(0)
	v_add_u32_e32 v16, v16, v5
	s_nop 2
	global_load_dword v6, v129, s[4:5] sc1
	v_readlane_b32 s4, v253, 25
	v_readlane_b32 s5, v253, 26
	s_waitcnt vmcnt(0)
	v_add_u32_e32 v16, v16, v6
	s_nop 2
	global_load_dword v7, v129, s[4:5] sc1
	v_readlane_b32 s4, v253, 27
	v_readlane_b32 s5, v253, 28
	s_waitcnt vmcnt(0)
	v_add_u32_e32 v16, v16, v7
	s_nop 2
	global_load_dword v8, v129, s[4:5] sc1
	v_readlane_b32 s4, v253, 29
	v_readlane_b32 s5, v253, 30
	s_waitcnt vmcnt(0)
	v_add_u32_e32 v16, v16, v8
	s_nop 2
	global_load_dword v9, v129, s[4:5] sc1
	v_readlane_b32 s4, v253, 31
	v_readlane_b32 s5, v253, 32
	s_waitcnt vmcnt(0)
	v_add_u32_e32 v16, v16, v9
	s_nop 2
	global_load_dword v10, v129, s[4:5] sc1
	v_readlane_b32 s4, v253, 33
	v_readlane_b32 s5, v253, 34
	s_waitcnt vmcnt(0)
	v_add_u32_e32 v16, v16, v10
	s_nop 2
	global_load_dword v11, v129, s[4:5] sc1
	v_readlane_b32 s4, v253, 35
	v_readlane_b32 s5, v253, 36
	s_waitcnt vmcnt(0)
	v_add_u32_e32 v16, v16, v11
	s_nop 2
	global_load_dword v12, v129, s[4:5] sc1
	v_readlane_b32 s4, v253, 37
	v_readlane_b32 s5, v253, 38
	s_waitcnt vmcnt(0)
	v_add_u32_e32 v16, v16, v12
	s_nop 2
	global_load_dword v13, v129, s[4:5] sc1
	v_readlane_b32 s4, v253, 39
	v_readlane_b32 s5, v253, 40
	s_waitcnt vmcnt(0)
	v_add_u32_e32 v16, v16, v13
	s_nop 2
	global_load_dword v14, v129, s[4:5] sc1
	v_readlane_b32 s4, v253, 41
	v_readlane_b32 s5, v253, 42
	s_waitcnt vmcnt(0)
	v_add_u32_e32 v16, v16, v14
	s_nop 2
	global_load_dword v15, v129, s[4:5] sc1
	s_waitcnt vmcnt(0)
	v_add_u32_e32 v16, v16, v15
	v_cmp_eq_u32_e32 vcc, s1, v16
	s_cbranch_vccnz .LBB0_512
	s_and_b32 s1, s0, 0xff
	s_cmp_eq_u32 s1, 0
	s_mov_b64 s[18:19], -1
	s_sleep 0
	s_cbranch_scc0 .LBB0_517
	v_readlane_b32 s4, v253, 9
	v_readlane_b32 s5, v253, 10
	s_nop 4
	global_load_dword v16, v129, s[4:5] sc1
	s_waitcnt vmcnt(0)
	v_cmp_eq_u32_e32 vcc, 0, v16
	s_cbranch_vccnz .LBB0_519
	s_mov_b64 s[18:19], 0

.LBB0_531:
	s_and_b32 s1, s0, 0xff
	s_mov_b64 s[34:35], -1
	s_cmp_lg_u32 s1, 0
	s_mov_b64 s[40:41], -1
	s_sleep 0
	s_cbranch_scc1 .LBB0_534
	v_readlane_b32 s4, v253, 9
	v_readlane_b32 s5, v253, 10
	s_nop 4
	global_load_dword v0, v129, s[4:5] sc1
	s_waitcnt vmcnt(0)
	v_cmp_eq_u32_e32 vcc, 0, v0
	s_cbranch_vccnz .LBB0_536
	s_mov_b64 s[40:41], 0
	s_mov_b64 s[38:39], -1
